# attention wave-0 tail: next-tile key positions prefetched at tile top, max via DPP+permlane instead of bpermute chain
# baseline (speedup 1.0000x reference)
.LBB0_214:
	s_add_i32 s49, s28, 1
	s_cmp_lt_u32 s49, s44
	s_cselect_b64 s[26:27], -1, 0
	s_cmp_ge_u32 s49, s44
	s_cbranch_scc1 .LBB0_216
	v_add_co_u32_e32 v64, vcc, 0xfff98000, v180
	s_nop 1
	v_addc_co_u32_e32 v65, vcc, -1, v181, vcc
	global_load_dwordx4 v[146:149], v[64:65], off offset:-1024
	global_load_dwordx4 v[150:153], v[64:65], off
	global_load_dwordx4 v[154:157], v[180:181], off offset:-1024
	global_load_dwordx4 v[158:161], v[180:181], off
	s_and_saveexec_b64 s[34:35], s[8:9]
	s_cbranch_execz .Lattn_pos_skip
	v_add_u32_e32 v222, s47, v230
	v_ashrrev_i32_e32 v223, 31, v222
	v_lshl_add_u64 v[222:223], v[222:223], 2, s[24:25]
	global_load_dword v194, v[222:223], off
.Lattn_pos_skip:
	s_or_b64 exec, exec, s[34:35]

.LBB0_229:
	s_xor_b32 s28, s50, 1
	s_lshl_b32 s26, s28, 15
	s_add_i32 s26, s26, 0
	v_add_u32_e32 v64, s26, v190
	v_add_u32_e32 v65, s26, v191
	s_waitcnt vmcnt(3)
	ds_write_b128 v64, v[146:149]
	s_waitcnt vmcnt(1)
	ds_write_b128 v65, v[154:157]
	ds_write_b128 v64, v[150:153] offset:16384
	s_waitcnt vmcnt(0)
	ds_write_b128 v65, v[158:161] offset:16384
	s_and_saveexec_b64 s[26:27], s[8:9]
	s_cbranch_execz .LBB0_232
	v_lshl_add_u32 v67, s28, 8, v192
	ds_write_b32 v67, v194
	v_mov_b32_e32 v64, v194
	s_nop 1
	v_max_i32_dpp v64, v64, v64 row_ror:8 row_mask:0xf bank_mask:0xf
	s_nop 1
	v_max_i32_dpp v64, v64, v64 row_ror:4 row_mask:0xf bank_mask:0xf
	s_nop 1
	v_max_i32_dpp v64, v64, v64 row_ror:2 row_mask:0xf bank_mask:0xf
	s_nop 1
	v_max_i32_dpp v64, v64, v64 row_ror:1 row_mask:0xf bank_mask:0xf
	v_mov_b32_e32 v65, v64
	s_nop 1
	v_permlane16_swap_b32_e32 v64, v65
	v_max_i32_e32 v64, v64, v65
	v_mov_b32_e32 v65, v64
	s_nop 1
	v_permlane32_swap_b32_e32 v64, v65
	v_max_i32_e32 v64, v64, v65
	s_and_b64 exec, exec, s[10:11]
	s_cbranch_execz .LBB0_232
	s_lshl_b32 s28, s28, 2
	s_add_i32 s28, s28, 0
	s_add_i32 s28, s28, 0x10410
	v_mov_b32_e32 v65, s28
	ds_write_b32 v65, v64
